# NSA selected sweep: branch-free loop top (tile select + ff1 search) and SGPR-base tile addressing (removes 2 v_mad_i64 + 6 VALU per tile)
# speedup vs baseline: 1.0166x; 1.0009x over previous
.LBB0_298:
	s_lshl_b32 s2, s46, 1
	v_lshl_add_u64 v[146:147], v[144:145], 0, s[2:3]
	v_lshl_add_u32 v2, s51, 6, v203
	s_movk_i32 s2, 0x1400
	v_lshlrev_b32_e32 v148, 3, v155
	v_mad_i64_i32 v[0:1], s[0:1], v2, s2, 0
	v_or_b32_e32 v0, v0, v148
	v_lshl_add_u64 v[0:1], v[0:1], 1, v[146:147]
	global_load_dwordx4 v[128:131], v[0:1], off offset:3072
	global_load_dwordx4 v[132:135], v[0:1], off offset:3584
	v_add_u32_e32 v0, 32, v2
	v_mad_i64_i32 v[0:1], s[0:1], v0, s2, 0
	v_or_b32_e32 v0, v0, v148
	v_lshl_add_u64 v[0:1], v[0:1], 1, v[146:147]
	global_load_dwordx4 v[136:139], v[0:1], off offset:3072
	global_load_dwordx4 v[140:143], v[0:1], off offset:3584
	v_lshlrev_b32_e32 v0, 2, v151
	v_or_b32_e32 v1, v0, v152
	v_lshlrev_b32_e32 v2, 3, v149
	v_mul_u32_u24_e32 v157, 0x90, v1
	v_lshlrev_b32_e32 v1, 1, v149
	v_and_b32_e32 v2, 24, v2
	v_and_or_b32 v158, v1, 32, v2
	v_lshrrev_b32_e32 v1, s20, v154
	v_lshl_or_b32 v0, s20, 6, v0
	v_and_b32_e32 v1, 1, v1
	v_cmp_eq_u32_e32 vcc, 1, v1
	v_cmp_le_u32_e64 s[4:5], v0, v206
	s_and_b64 s[18:19], vcc, s[4:5]
	v_cmp_lt_u32_e64 s[4:5], v0, v206
	v_or_b32_e32 v1, 2, v0
	s_and_b64 s[22:23], vcc, s[4:5]
	v_cmp_le_u32_e64 s[4:5], v1, v206
	v_or_b32_e32 v1, 3, v0
	s_and_b64 s[34:35], vcc, s[4:5]
	v_cmp_le_u32_e64 s[4:5], v1, v206
	v_or_b32_e32 v1, 8, v0
	s_and_b64 s[40:41], vcc, s[4:5]
	v_cmp_le_u32_e64 s[4:5], v1, v206
	v_or_b32_e32 v1, 9, v0
	s_and_b64 s[54:55], vcc, s[4:5]
	v_cmp_le_u32_e64 s[4:5], v1, v206
	v_or_b32_e32 v1, 10, v0
	s_and_b64 s[58:59], vcc, s[4:5]
	v_cmp_le_u32_e64 s[4:5], v1, v206
	v_or_b32_e32 v1, 11, v0
	s_and_b64 s[64:65], vcc, s[4:5]
	v_cmp_le_u32_e64 s[4:5], v1, v206
	v_or_b32_e32 v1, 16, v0
	s_and_b64 s[28:29], vcc, s[4:5]
	v_cmp_le_u32_e64 s[4:5], v1, v206
	v_or_b32_e32 v1, 17, v0
	s_and_b64 s[24:25], vcc, s[4:5]
	v_cmp_le_u32_e64 s[4:5], v1, v206
	v_or_b32_e32 v1, 18, v0
	s_and_b64 s[62:63], vcc, s[4:5]
	v_cmp_le_u32_e64 s[4:5], v1, v206
	v_or_b32_e32 v1, 19, v0
	s_and_b64 s[66:67], vcc, s[4:5]
	v_cmp_le_u32_e64 s[4:5], v1, v206
	v_or_b32_e32 v1, 24, v0
	s_and_b64 s[68:69], vcc, s[4:5]
	v_cmp_le_u32_e64 s[4:5], v1, v206
	v_or_b32_e32 v1, 25, v0
	s_and_b64 s[16:17], vcc, s[4:5]
	v_cmp_le_u32_e64 s[4:5], v1, v206
	v_or_b32_e32 v1, 26, v0
	s_and_b64 s[52:53], vcc, s[4:5]
	v_cmp_le_u32_e64 s[4:5], v1, v206
	v_or_b32_e32 v1, 27, v0
	s_and_b64 s[70:71], vcc, s[4:5]
	v_cmp_le_u32_e64 s[4:5], v1, v206
	v_or_b32_e32 v1, 32, v0
	s_and_b64 s[72:73], vcc, s[4:5]
	v_cmp_le_u32_e64 s[4:5], v1, v206
	v_or_b32_e32 v1, 33, v0
	s_and_b64 s[74:75], vcc, s[4:5]
	v_cmp_le_u32_e64 s[4:5], v1, v206
	v_or_b32_e32 v1, 34, v0
	s_and_b64 s[76:77], vcc, s[4:5]
	v_cmp_le_u32_e64 s[4:5], v1, v206
	v_or_b32_e32 v1, 35, v0
	s_and_b64 s[78:79], vcc, s[4:5]
	v_cmp_le_u32_e64 s[4:5], v1, v206
	v_or_b32_e32 v1, 40, v0
	v_writelane_b32 v248, s46, 38
	s_and_b64 s[60:61], vcc, s[4:5]
	v_cmp_le_u32_e64 s[4:5], v1, v206
	v_or_b32_e32 v1, 41, v0
	s_and_b64 s[82:83], vcc, s[4:5]
	v_cmp_le_u32_e64 s[4:5], v1, v206
	v_or_b32_e32 v1, 42, v0
	v_writelane_b32 v248, s40, 39
	s_and_b64 s[84:85], vcc, s[4:5]
	v_cmp_le_u32_e64 s[4:5], v1, v206
	v_or_b32_e32 v1, 43, v0
	v_writelane_b32 v248, s41, 40
	s_and_b64 s[86:87], vcc, s[4:5]
	v_cmp_le_u32_e64 s[4:5], v1, v206
	v_or_b32_e32 v1, 48, v0
	v_writelane_b32 v248, s28, 41
	s_and_b64 s[88:89], vcc, s[4:5]
	v_cmp_le_u32_e64 s[4:5], v1, v206
	v_or_b32_e32 v1, 49, v0
	v_writelane_b32 v248, s29, 42
	s_and_b64 s[90:91], vcc, s[4:5]
	v_cmp_le_u32_e64 s[4:5], v1, v206
	v_or_b32_e32 v1, 50, v0
	v_writelane_b32 v248, s24, 43
	s_and_b64 s[92:93], vcc, s[4:5]
	v_cmp_le_u32_e64 s[4:5], v1, v206
	v_or_b32_e32 v1, 51, v0
	v_writelane_b32 v248, s25, 44
	s_and_b64 s[94:95], vcc, s[4:5]
	v_cmp_le_u32_e64 s[4:5], v1, v206
	v_or_b32_e32 v1, 56, v0
	v_writelane_b32 v248, s68, 45
	s_and_b64 s[96:97], vcc, s[4:5]
	v_cmp_le_u32_e64 s[4:5], v1, v206
	v_or_b32_e32 v1, 57, v0
	v_writelane_b32 v248, s69, 46
	v_cmp_le_u32_e64 s[6:7], v1, v206
	v_or_b32_e32 v1, 58, v0
	v_or_b32_e32 v0, 59, v0
	v_writelane_b32 v248, s66, 47
	v_cmp_le_u32_e64 s[8:9], v1, v206
	v_cmp_le_u32_e64 s[10:11], v0, v206
	v_xor_b32_e32 v0, 32, v219
	v_writelane_b32 v248, s67, 48
	s_and_b64 s[4:5], vcc, s[4:5]
	s_and_b64 s[6:7], vcc, s[6:7]
	s_and_b64 s[8:9], vcc, s[8:9]
	s_and_b64 s[56:57], vcc, s[10:11]
	v_cmp_lt_i32_e32 vcc, v0, v153
	v_writelane_b32 v248, s34, 49
	s_movk_i32 s0, 0x90
	v_cndmask_b32_e32 v0, v219, v0, vcc
	v_mov_b32_e32 v179, 0
	v_writelane_b32 v248, s35, 50
	v_lshlrev_b32_e32 v156, 4, v155
	v_mul_lo_u32 v159, v203, s0
	v_lshlrev_b32_e32 v176, 2, v0
	s_mov_b32 s2, s33
	s_mov_b32 s44, s33
	s_mov_b32 s45, s33
	s_mov_b32 s46, s33
	s_mov_b32 s47, s33
	s_mov_b32 s48, s33
	s_mov_b32 s49, s33
	v_mov_b32_e32 v180, 0xf149f2ca
	v_mov_b32_e32 v177, 0
	v_mov_b32_e32 v80, 0
	v_mov_b32_e32 v81, v179
	v_mov_b32_e32 v82, v179
	v_mov_b32_e32 v83, v179
	v_mov_b32_e32 v84, v179
	v_mov_b32_e32 v85, v179
	v_mov_b32_e32 v86, v179
	v_mov_b32_e32 v87, v179
	v_mov_b32_e32 v88, v179
	v_mov_b32_e32 v89, v179
	v_mov_b32_e32 v90, v179
	v_mov_b32_e32 v91, v179
	v_mov_b32_e32 v92, v179
	v_mov_b32_e32 v93, v179
	v_mov_b32_e32 v94, v179
	v_mov_b32_e32 v95, v179
	v_mov_b32_e32 v64, 0
	v_mov_b32_e32 v65, v179
	v_mov_b32_e32 v66, v179
	v_mov_b32_e32 v67, v179
	v_mov_b32_e32 v68, v179
	v_mov_b32_e32 v69, v179
	v_mov_b32_e32 v70, v179
	v_mov_b32_e32 v71, v179
	v_mov_b32_e32 v72, v179
	v_mov_b32_e32 v73, v179
	v_mov_b32_e32 v74, v179
	v_mov_b32_e32 v75, v179
	v_mov_b32_e32 v76, v179
	v_mov_b32_e32 v77, v179
	v_mov_b32_e32 v78, v179
	v_mov_b32_e32 v79, v179
	v_writelane_b32 v248, s62, 51
	s_nop 1
	v_writelane_b32 v248, s63, 52
	v_readfirstlane_b32 s98, v146
	v_readfirstlane_b32 s99, v147
	v_mul_u32_u24_e32 v186, 0x2800, v203
	v_lshl_add_u32 v186, v148, 1, v186
	v_add_u32_e32 v187, 0x50000, v186
.LBB0_299:
	s_cmp_lt_i32 s42, s12
	v_mul_u32_u24_e32 v178, 0x4800, v177
	s_cselect_b64 s[36:37], -1, 0
	s_cselect_b32 s0, s51, s12
	s_mov_b32 s50, s12
	v_add3_u32 v0, v178, v156, v159
	s_not_b64 s[38:39], s[36:37]
	s_add_i32 s12, s12, 1
	s_lshr_b32 s1, s33, s12
	s_ff1_i32_b32 s1, s1
	s_cmp_lt_i32 s1, 0
	s_cselect_b32 s1, 32, s1
	s_add_i32 s12, s12, s1
	s_add_i32 s1, s42, 1
	s_min_i32 s12, s12, s1
	s_waitcnt vmcnt(3)
	ds_write_b128 v0, v[128:131]
	s_waitcnt vmcnt(2)
	ds_write_b128 v0, v[132:135] offset:9216
	s_waitcnt vmcnt(1)
	ds_write_b128 v0, v[136:139] offset:4608
	s_waitcnt vmcnt(0)
	ds_write_b128 v0, v[140:143] offset:13824
	s_waitcnt lgkmcnt(0)
	s_barrier
.LBB0_317:
	s_mul_i32 s13, s0, 0xa0000
	v_add3_u32 v8, v178, v201, v202
	s_add_u32 s100, s98, s13
	s_addc_u32 s101, s99, 0
	ds_read_b128 v[0:3], v8
	ds_read_b128 v[4:7], v8 offset:32
	ds_read_b128 v[12:15], v8 offset:64
	ds_read_b128 v[16:19], v8 offset:96
	ds_read_b128 v[20:23], v8 offset:4608
	ds_read_b128 v[24:27], v8 offset:4640
	ds_read_b128 v[28:31], v8 offset:4672
	ds_read_b128 v[8:11], v8 offset:4704
	global_load_dwordx4 v[128:131], v186, s[100:101] offset:3072
	global_load_dwordx4 v[132:135], v186, s[100:101] offset:3584
	global_load_dwordx4 v[136:139], v187, s[100:101] offset:3072
	global_load_dwordx4 v[140:143], v187, s[100:101] offset:3584
	s_mov_b64 s[14:15], -1
	s_cmp_lg_u32 s51, s20
	s_waitcnt lgkmcnt(7)
	v_mfma_f32_32x32x16_bf16 v[112:127], v[0:3], v[160:163], 0
	s_waitcnt lgkmcnt(6)
	v_mfma_f32_32x32x16_bf16 v[112:127], v[4:7], v[164:167], v[112:127]
	s_waitcnt lgkmcnt(5)
	v_mfma_f32_32x32x16_bf16 v[112:127], v[12:15], v[168:171], v[112:127]
	s_waitcnt lgkmcnt(4)
	v_mfma_f32_32x32x16_bf16 v[112:127], v[16:19], v[172:175], v[112:127]
	s_waitcnt lgkmcnt(3)
	v_mfma_f32_32x32x16_bf16 v[96:111], v[20:23], v[160:163], 0
	s_waitcnt lgkmcnt(2)
	v_mfma_f32_32x32x16_bf16 v[96:111], v[24:27], v[164:167], v[96:111]
	s_waitcnt lgkmcnt(1)
	v_mfma_f32_32x32x16_bf16 v[96:111], v[28:31], v[168:171], v[96:111]
	s_waitcnt lgkmcnt(0)
	v_mfma_f32_32x32x16_bf16 v[96:111], v[8:11], v[172:175], v[96:111]
	s_cbranch_scc0 .LBB0_319
	s_nop 10
	v_max_f32_e32 v0, v96, v96
	v_max_f32_e32 v1, v112, v112
	v_max_f32_e32 v0, v1, v0
	v_max3_f32 v0, v0, v113, v97
	v_max3_f32 v0, v0, v114, v98
	v_max3_f32 v0, v0, v115, v99
	v_max3_f32 v0, v0, v116, v100
	v_max3_f32 v0, v0, v117, v101
	v_max3_f32 v0, v0, v118, v102
	v_max3_f32 v0, v0, v119, v103
	v_max3_f32 v0, v0, v120, v104
	v_max3_f32 v0, v0, v121, v105
	v_max3_f32 v0, v0, v122, v106
	v_max3_f32 v0, v0, v123, v107
	v_max3_f32 v0, v0, v124, v108
	v_max3_f32 v0, v0, v125, v109
	v_max3_f32 v0, v0, v126, v110
	v_max3_f32 v0, v0, v127, v111
	v_mov_b32_e32 v1, v0
	v_bfe_u32 v2, v154, s51, 1
	v_cmp_eq_u32_e32 vcc, 0, v2
	v_max_f32_e32 v3, v180, v180
	s_mov_b64 s[14:15], 0
	v_permlane32_swap_b32_e32 v0, v1
	v_max_f32_e32 v1, v1, v1
	v_max_f32_e32 v0, v0, v1
	v_mul_f32_e32 v0, 0x3e38aa3b, v0
	v_cndmask_b32_e32 v0, v0, v215, vcc
	v_max_f32_e32 v181, v3, v0
	v_sub_f32_e32 v0, v180, v181
	v_cndmask_b32_e64 v30, v232, 0, vcc
	v_cndmask_b32_e64 v182, -v181, v215, vcc
	v_exp_f32_e32 v150, v0
	v_pk_fma_f32 v[0:1], v[30:31], v[112:113], v[182:183] op_sel_hi:[0,1,0]
	v_exp_f32_e32 v0, v0
	v_exp_f32_e32 v1, v1
	v_pk_fma_f32 v[2:3], v[30:31], v[114:115], v[182:183] op_sel_hi:[0,1,0]
	v_exp_f32_e32 v2, v2
	v_exp_f32_e32 v3, v3
	v_pk_fma_f32 v[4:5], v[30:31], v[116:117], v[182:183] op_sel_hi:[0,1,0]
	v_exp_f32_e32 v4, v4
	v_exp_f32_e32 v5, v5
	v_pk_fma_f32 v[6:7], v[30:31], v[118:119], v[182:183] op_sel_hi:[0,1,0]
	v_exp_f32_e32 v6, v6
	v_exp_f32_e32 v7, v7
	v_pk_add_f32 v[8:9], v[0:1], 0 op_sel_hi:[1,0]
	v_pk_fma_f32 v[10:11], v[30:31], v[122:123], v[182:183] op_sel_hi:[0,1,0]
	v_pk_add_f32 v[8:9], v[2:3], v[8:9]
	v_exp_f32_e32 v10, v10
	v_pk_add_f32 v[8:9], v[4:5], v[8:9]
	v_exp_f32_e32 v11, v11
	v_pk_add_f32 v[16:17], v[6:7], v[8:9]
	v_pk_fma_f32 v[8:9], v[30:31], v[120:121], v[182:183] op_sel_hi:[0,1,0]
	v_exp_f32_e32 v8, v8
	v_exp_f32_e32 v9, v9
	v_pk_fma_f32 v[12:13], v[30:31], v[124:125], v[182:183] op_sel_hi:[0,1,0]
	v_exp_f32_e32 v12, v12
	v_exp_f32_e32 v13, v13
	v_pk_fma_f32 v[14:15], v[30:31], v[126:127], v[182:183] op_sel_hi:[0,1,0]
	v_exp_f32_e32 v14, v14
	v_exp_f32_e32 v15, v15
	v_pk_add_f32 v[16:17], v[8:9], v[16:17]
	v_pk_fma_f32 v[18:19], v[30:31], v[98:99], v[182:183] op_sel_hi:[0,1,0]
	v_pk_add_f32 v[16:17], v[10:11], v[16:17]
	v_exp_f32_e32 v18, v18
	v_pk_add_f32 v[16:17], v[12:13], v[16:17]
	v_exp_f32_e32 v19, v19
	v_pk_add_f32 v[24:25], v[14:15], v[16:17]
	v_pk_fma_f32 v[16:17], v[30:31], v[96:97], v[182:183] op_sel_hi:[0,1,0]
	v_exp_f32_e32 v16, v16
	v_exp_f32_e32 v17, v17
	v_pk_fma_f32 v[20:21], v[30:31], v[100:101], v[182:183] op_sel_hi:[0,1,0]
	v_exp_f32_e32 v20, v20
	v_exp_f32_e32 v21, v21
	v_pk_fma_f32 v[22:23], v[30:31], v[102:103], v[182:183] op_sel_hi:[0,1,0]
	v_exp_f32_e32 v22, v22
	v_exp_f32_e32 v23, v23
	v_pk_add_f32 v[24:25], v[16:17], v[24:25]
	v_pk_fma_f32 v[26:27], v[30:31], v[106:107], v[182:183] op_sel_hi:[0,1,0]
	v_pk_add_f32 v[24:25], v[18:19], v[24:25]
	v_exp_f32_e32 v26, v26
	v_pk_add_f32 v[24:25], v[20:21], v[24:25]
	v_exp_f32_e32 v27, v27
	v_pk_add_f32 v[184:185], v[22:23], v[24:25]
	v_pk_fma_f32 v[24:25], v[30:31], v[104:105], v[182:183] op_sel_hi:[0,1,0]
	v_exp_f32_e32 v24, v24
	v_exp_f32_e32 v25, v25
	v_pk_fma_f32 v[28:29], v[30:31], v[108:109], v[182:183] op_sel_hi:[0,1,0]
	v_exp_f32_e32 v28, v28
	v_exp_f32_e32 v29, v29
	v_pk_fma_f32 v[30:31], v[30:31], v[110:111], v[182:183] op_sel_hi:[0,1,0]
	v_exp_f32_e32 v30, v30
	v_exp_f32_e32 v31, v31
	v_pk_add_f32 v[182:183], v[24:25], v[184:185]
	s_nop 0
	v_pk_add_f32 v[182:183], v[26:27], v[182:183]
	s_nop 0
	v_pk_add_f32 v[182:183], v[28:29], v[182:183]
	s_nop 0
	v_pk_add_f32 v[182:183], v[30:31], v[182:183]
	s_nop 0
	v_add_f32_e32 v182, v182, v183

	.amdhsa_kernel _Z10hybrid_fwd6Paramsiiy
		.amdhsa_group_segment_fixed_size 0
		.amdhsa_private_segment_fixed_size 0
		.amdhsa_kernarg_size 704
		.amdhsa_user_sgpr_count 2
		.amdhsa_user_sgpr_dispatch_ptr 0
		.amdhsa_user_sgpr_queue_ptr 0
		.amdhsa_user_sgpr_kernarg_segment_ptr 1
		.amdhsa_user_sgpr_dispatch_id 0
		.amdhsa_user_sgpr_kernarg_preload_length 0
		.amdhsa_user_sgpr_kernarg_preload_offset 0
		.amdhsa_user_sgpr_private_segment_size 0
		.amdhsa_uses_dynamic_stack 0
		.amdhsa_enable_private_segment 0
		.amdhsa_system_sgpr_workgroup_id_x 1
		.amdhsa_system_sgpr_workgroup_id_y 0
		.amdhsa_system_sgpr_workgroup_id_z 0
		.amdhsa_system_sgpr_workgroup_info 0
		.amdhsa_system_vgpr_workitem_id 2
		.amdhsa_next_free_vgpr 252
		.amdhsa_next_free_sgpr 102
		.amdhsa_accum_offset 252
		.amdhsa_reserve_vcc 1
		.amdhsa_float_round_mode_32 0
		.amdhsa_float_round_mode_16_64 0
		.amdhsa_float_denorm_mode_32 3
		.amdhsa_float_denorm_mode_16_64 3
		.amdhsa_dx10_clamp 1
		.amdhsa_ieee_mode 1
		.amdhsa_fp16_overflow 0
		.amdhsa_tg_split 0
		.amdhsa_exception_fp_ieee_invalid_op 0
		.amdhsa_exception_fp_denorm_src 0
		.amdhsa_exception_fp_ieee_div_zero 0
		.amdhsa_exception_fp_ieee_overflow 0
		.amdhsa_exception_fp_ieee_underflow 0
		.amdhsa_exception_fp_ieee_inexact 0
		.amdhsa_exception_int_div_zero 0
	.end_amdhsa_kernel

amdhsa.kernels:
  - .agpr_count:     0
    .args:
      - .offset:         0
        .size:           432
        .value_kind:     by_value
      - .offset:         432
        .size:           4
        .value_kind:     by_value
      - .offset:         436
        .size:           4
        .value_kind:     by_value
      - .offset:         440
        .size:           8
        .value_kind:     by_value
      - .offset:         448
        .size:           4
        .value_kind:     hidden_block_count_x
      - .offset:         452
        .size:           4
        .value_kind:     hidden_block_count_y
      - .offset:         456
        .size:           4
        .value_kind:     hidden_block_count_z
      - .offset:         460
        .size:           2
        .value_kind:     hidden_group_size_x
      - .offset:         462
        .size:           2
        .value_kind:     hidden_group_size_y
      - .offset:         464
        .size:           2
        .value_kind:     hidden_group_size_z
      - .offset:         466
        .size:           2
        .value_kind:     hidden_remainder_x
      - .offset:         468
        .size:           2
        .value_kind:     hidden_remainder_y
      - .offset:         470
        .size:           2
        .value_kind:     hidden_remainder_z
      - .offset:         488
        .size:           8
        .value_kind:     hidden_global_offset_x
      - .offset:         496
        .size:           8
        .value_kind:     hidden_global_offset_y
      - .offset:         504
        .size:           8
        .value_kind:     hidden_global_offset_z
      - .offset:         512
        .size:           2
        .value_kind:     hidden_grid_dims
      - .offset:         536
        .size:           8
        .value_kind:     hidden_multigrid_sync_arg
      - .offset:         568
        .size:           4
        .value_kind:     hidden_dynamic_lds_size
    .group_segment_fixed_size: 0
    .kernarg_segment_align: 8
    .kernarg_segment_size: 704
    .language:       OpenCL C
    .language_version:
      - 2
      - 0
    .max_flat_workgroup_size: 256
    .name:           _Z10hybrid_fwd6Paramsiiy
    .private_segment_fixed_size: 0
    .sgpr_count:     108
    .sgpr_spill_count: 255
    .symbol:         _Z10hybrid_fwd6Paramsiiy.kd
    .uniform_work_group_size: 1
    .uses_dynamic_stack: false
    .vgpr_count:     252
    .vgpr_spill_count: 0
    .wavefront_size: 64
